# P10 non-diagonal tiles: the 16 exps of S0 issued during the S1 row-max chain when S0 is below the rescale threshold; PV fillers carry only S1 exps, sums and cvts
# speedup vs baseline: 1.0014x; 1.0014x over previous
.Lfa_nodiag:
	v_cmp_lt_f32_e32 vcc, s79, v243
	s_cbranch_vccnz .Lfa_nd_old
	s_mul_i32 s33, s87, 0x4800
	v_add_u32_e32 v211, s33, v151
	ds_read_b128 v[232:235], v211 offset:51200
	ds_read_b128 v[202:205], v211 offset:55808
	ds_read_b128 v[206:209], v211 offset:60416
	ds_read_b128 v[244:247], v211 offset:65024
	v_exp_f32_e32 v168, v80
	v_exp_f32_e32 v169, v81
	v_exp_f32_e32 v170, v82
	v_exp_f32_e32 v171, v83
	v_exp_f32_e32 v172, v84
	v_exp_f32_e32 v173, v85
	v_max3_f32 v144, v243, v64, v65
	v_exp_f32_e32 v174, v86
	v_max3_f32 v144, v144, v66, v67
	v_exp_f32_e32 v175, v87
	v_max3_f32 v144, v144, v68, v69
	v_exp_f32_e32 v176, v88
	v_max3_f32 v144, v144, v70, v71
	v_exp_f32_e32 v177, v89
	v_max3_f32 v144, v144, v72, v73
	v_exp_f32_e32 v178, v90
	v_max3_f32 v144, v144, v74, v75
	v_exp_f32_e32 v179, v91
	v_max3_f32 v144, v144, v76, v77
	v_exp_f32_e32 v180, v92
	v_max3_f32 v144, v144, v78, v79
	v_exp_f32_e32 v181, v93
	v_exp_f32_e32 v182, v94
	v_exp_f32_e32 v183, v95
	v_mov_b32_e32 v210, v144
	v_mov_b32_e32 v243, v144
	s_nop 1
	v_permlane32_swap_b32_e32 v210, v243
	v_max_f32_e32 v144, v210, v243
	v_cmp_lt_f32_e32 vcc, s79, v144
	s_cbranch_vccnz .Lfa_rare
	s_waitcnt lgkmcnt(3)
	v_mfma_f32_32x32x16_bf16 v[48:63], v[232:235], v[216:219], v[48:63]
	ds_read_b128 v[232:235], v211 offset:51232
	v_exp_f32_e32 v64, v64
	v_add_f32_e32 v194, v194, v168
	v_add_f32_e32 v195, v195, v169
	v_add_f32_e32 v196, v196, v170
	v_add_f32_e32 v197, v197, v171
	s_waitcnt lgkmcnt(3)
	v_mfma_f32_32x32x16_bf16 v[32:47], v[202:205], v[216:219], v[32:47]
	ds_read_b128 v[202:205], v211 offset:55840
	v_exp_f32_e32 v65, v65
	v_add_f32_e32 v194, v194, v172
	v_add_f32_e32 v195, v195, v173
	v_add_f32_e32 v196, v196, v174
	v_add_f32_e32 v197, v197, v175
	s_waitcnt lgkmcnt(3)
	v_mfma_f32_32x32x16_bf16 v[16:31], v[206:209], v[216:219], v[16:31]
	ds_read_b128 v[206:209], v211 offset:60448
	v_exp_f32_e32 v66, v66
	v_add_f32_e32 v194, v194, v176
	v_add_f32_e32 v195, v195, v177
	v_add_f32_e32 v196, v196, v178
	v_add_f32_e32 v197, v197, v179
	v_add_f32_e32 v194, v194, v64
	v_add_f32_e32 v195, v195, v65
	s_waitcnt lgkmcnt(3)
	v_mfma_f32_32x32x16_bf16 v[0:15], v[244:247], v[216:219], v[0:15]
	ds_read_b128 v[244:247], v211 offset:65056
	v_exp_f32_e32 v67, v67
	v_add_f32_e32 v194, v194, v180
	v_add_f32_e32 v195, v195, v181
	v_add_f32_e32 v196, v196, v182
	v_add_f32_e32 v197, v197, v183
	s_waitcnt lgkmcnt(3)
	v_mfma_f32_32x32x16_bf16 v[48:63], v[232:235], v[220:223], v[48:63]
	ds_read_b128 v[232:235], v211 offset:51264
	v_exp_f32_e32 v68, v68
	v_add_f32_e32 v196, v196, v66
	v_add_f32_e32 v197, v197, v67
	v_cvt_pk_bf16_f32 v216, v168, v169
	s_waitcnt lgkmcnt(3)
	v_mfma_f32_32x32x16_bf16 v[32:47], v[202:205], v[220:223], v[32:47]
	ds_read_b128 v[202:205], v211 offset:55872
	v_exp_f32_e32 v69, v69
	v_cvt_pk_bf16_f32 v217, v170, v171
	s_waitcnt lgkmcnt(3)
	v_mfma_f32_32x32x16_bf16 v[16:31], v[206:209], v[220:223], v[16:31]
	ds_read_b128 v[206:209], v211 offset:60480
	v_exp_f32_e32 v70, v70
	v_add_f32_e32 v194, v194, v68
	v_add_f32_e32 v195, v195, v69
	v_cvt_pk_bf16_f32 v218, v172, v173
	s_waitcnt lgkmcnt(3)
	v_mfma_f32_32x32x16_bf16 v[0:15], v[244:247], v[220:223], v[0:15]
	ds_read_b128 v[244:247], v211 offset:65088
	v_exp_f32_e32 v71, v71
	v_cvt_pk_bf16_f32 v219, v174, v175
	s_waitcnt lgkmcnt(3)
	v_mfma_f32_32x32x16_bf16 v[48:63], v[232:235], v[224:227], v[48:63]
	ds_read_b128 v[232:235], v211 offset:51296
	v_exp_f32_e32 v72, v72
	v_add_f32_e32 v196, v196, v70
	v_add_f32_e32 v197, v197, v71
	v_cvt_pk_bf16_f32 v220, v176, v177
	s_waitcnt lgkmcnt(3)
	v_mfma_f32_32x32x16_bf16 v[32:47], v[202:205], v[224:227], v[32:47]
	ds_read_b128 v[202:205], v211 offset:55904
	v_exp_f32_e32 v73, v73
	v_cvt_pk_bf16_f32 v221, v178, v179
	s_waitcnt lgkmcnt(3)
	v_mfma_f32_32x32x16_bf16 v[16:31], v[206:209], v[224:227], v[16:31]
	ds_read_b128 v[206:209], v211 offset:60512
	v_exp_f32_e32 v74, v74
	v_add_f32_e32 v194, v194, v72
	v_add_f32_e32 v195, v195, v73
	v_cvt_pk_bf16_f32 v222, v180, v181
	s_waitcnt lgkmcnt(3)
	v_mfma_f32_32x32x16_bf16 v[0:15], v[244:247], v[224:227], v[0:15]
	ds_read_b128 v[244:247], v211 offset:65120
	v_exp_f32_e32 v75, v75
	v_cvt_pk_bf16_f32 v223, v182, v183
	s_waitcnt lgkmcnt(3)
	v_mfma_f32_32x32x16_bf16 v[48:63], v[232:235], v[228:231], v[48:63]
	v_exp_f32_e32 v76, v76
	v_add_f32_e32 v196, v196, v74
	v_add_f32_e32 v197, v197, v75
	v_cvt_pk_bf16_f32 v224, v64, v65
	s_waitcnt lgkmcnt(2)
	v_mfma_f32_32x32x16_bf16 v[32:47], v[202:205], v[228:231], v[32:47]
	v_exp_f32_e32 v77, v77
	v_cvt_pk_bf16_f32 v225, v66, v67
	s_waitcnt lgkmcnt(1)
	v_mfma_f32_32x32x16_bf16 v[16:31], v[206:209], v[228:231], v[16:31]
	v_exp_f32_e32 v78, v78
	v_add_f32_e32 v194, v194, v76
	v_add_f32_e32 v195, v195, v77
	v_cvt_pk_bf16_f32 v226, v68, v69
	s_waitcnt lgkmcnt(0)
	v_mfma_f32_32x32x16_bf16 v[0:15], v[244:247], v[228:231], v[0:15]
	v_exp_f32_e32 v79, v79
	v_cvt_pk_bf16_f32 v227, v70, v71
	v_add_f32_e32 v196, v196, v78
	v_add_f32_e32 v197, v197, v79
	v_cvt_pk_bf16_f32 v228, v72, v73
	v_cvt_pk_bf16_f32 v229, v74, v75
	v_cvt_pk_bf16_f32 v230, v76, v77
	v_cvt_pk_bf16_f32 v231, v78, v79
	s_mov_b32 s88, 1
	s_branch .LBB0_1332
